# P1 deferred single-copy loop, split point T=5632 (all WGs one item each of [5632,7680); one-unit-fewer WGs take [0,5632))
# baseline (speedup 1.0000x reference)
; __global__ void __launch_bounds__(NTHR, 2) mk_fwd(Args a) {
;     ...
;     {
;         constexpr int NU1 = (M / 256) * (2 * DFF / 256);
;         const int rounds = (NU1 + G - 1) / G, idle0 = NU1 - (rounds - 1) * G;
;         if (idle0 >= G) p0_deferred(P, lds, gw, NGW, wave, lane);
;         else if ((int)blockIdx.x >= idle0) p0_deferred(P, lds, ((int)blockIdx.x - idle0) * NWAVES + wave, (G - idle0) * NWAVES, wave, lane);
.LBB0_106:
	s_lshl_b32 s0, s87, 9
	s_add_u32 s72, s90, 0xc00000
	s_addc_u32 s73, s91, 0
	v_writelane_b32 v254, s0, 41
	s_add_u32 s0, s90, 0x1800000
	s_addc_u32 s1, s91, 0
	v_writelane_b32 v254, s0, 42
	s_nop 1
	v_writelane_b32 v254, s1, 43
	s_add_u32 s0, s90, 0x2500000
	s_addc_u32 s1, s91, 0
	s_add_u32 s94, s90, 0x2b00000
	s_addc_u32 s95, s91, 0
	s_add_u32 s96, s90, 0x1200000
	v_writelane_b32 v254, s0, 44
	s_addc_u32 s97, s91, 0
	s_nop 0
	v_writelane_b32 v254, s1, 45
	s_add_u32 s0, s90, 0x1a00000
	s_addc_u32 s1, s91, 0
	v_writelane_b32 v254, s0, 46
	s_nop 1
	v_writelane_b32 v254, s1, 47
	s_abs_i32 s0, s87
	s_waitcnt vmcnt(4)
	v_cvt_f32_u32_e32 v2, s0
	s_add_i32 s1, s87, 0x5ab
	s_xor_b32 s2, s1, s87
	s_sub_i32 s3, 0, s0
	v_rcp_iflag_f32_e32 v2, v2
	s_ashr_i32 s29, s2, 31
	s_abs_i32 s1, s1
	v_mul_f32_e32 v2, 0x4f7ffffe, v2
	v_cvt_u32_f32_e32 v2, v2
	s_nop 0
	v_readfirstlane_b32 s2, v2
	s_mul_i32 s3, s3, s2
	s_mul_hi_u32 s3, s2, s3
	s_add_i32 s2, s2, s3
	s_mul_hi_u32 s2, s1, s2
	s_mul_i32 s3, s2, s0
	s_sub_i32 s1, s1, s3
	s_add_i32 s4, s2, 1
	s_sub_i32 s3, s1, s0
	s_cmp_ge_u32 s1, s0
	s_cselect_b32 s2, s4, s2
	s_cselect_b32 s1, s3, s1
	s_add_i32 s3, s2, 1
	s_cmp_ge_u32 s1, s0
	s_cselect_b32 s0, s3, s2
	s_xor_b32 s30, s0, s29
	s_sub_i32 s0, s30, s29
	v_writelane_b32 v254, s0, 48
	s_add_i32 s0, s0, -1
	s_mul_i32 s0, s0, s87
	v_writelane_b32 v254, s0, 49
	s_sub_i32 s0, 0x5ac, s0
	s_cmp_le_i32 s87, s0
	s_cselect_b64 s[2:3], -1, 0
	v_writelane_b32 v254, s2, 50
	s_cmp_gt_i32 s87, s0
	s_nop 0
	v_writelane_b32 v254, s3, 51
	v_writelane_b32 v254, s0, 52
	s_mov_b64 s[0:1], -1
	s_movk_i32 s99, 0x1e00
	s_movk_i32 s100, 0x1dff
	s_mov_b32 s98, 0
	s_cbranch_scc0 .Lp1_gen
	s_movk_i32 s98, 0x1600

; __global__ void __launch_bounds__(NTHR, 2) mk_fwd(Args a) {
;     ...
;         if (idle0 >= G) p0_deferred(P, lds, gw, NGW, wave, lane);
;         else if ((int)blockIdx.x >= idle0) p0_deferred(P, lds, ((int)blockIdx.x - idle0) * NWAVES + wave, (G - idle0) * NWAVES, wave, lane);
.LBB0_226:
	s_or_b64 exec, exec, s[0:1]
	s_cmp_eq_u32 s98, 0
	s_cbranch_scc1 .LBB0_349
	v_readlane_b32 s0, v254, 52
	s_cmp_lt_i32 s86, s0
	s_cbranch_scc1 .LBB0_349
	s_sub_i32 s1, s86, s0
	s_lshl_b32 s1, s1, 3
	v_readlane_b32 s2, v254, 34
	s_add_i32 s1, s1, s2
	s_sub_i32 s0, s87, s0
	s_lshl_b32 s69, s0, 3
	s_movk_i32 s99, 0x1600
	s_movk_i32 s100, 0x15ff
	s_mov_b32 s98, 1
	s_nop 3
	v_writelane_b32 v254, s1, 35
	s_nop 3
	s_branch .Lp1_gen2
